# prologue de-serialisation: all 14 first-tile staging DMAs issued up front in P1/P5/P6 (on top of the w_down-in-P1 stack)
# baseline (speedup 1.0000x reference)
;     __device__ __forceinline__ unsigned voffA(int R, int C) const { return (unsigned)(R * lda + C) * 2u; }
;     __device__ __forceinline__ unsigned voffB(int R, int C) const { return (unsigned)(R * ldb + C) * 2u; }
;     __device__ __forceinline__ size_t hA() const { return (size_t)HALF * lda * 2; }
;     __device__ __forceinline__ size_t hB() const { return (size_t)HALF * ldb * 2; }
;     __device__ __forceinline__ const char* a(const Unit& u) const { return (const char*)A + (size_t)u.pm * 2 * hA(); }
;     __device__ __forceinline__ const char* b(const Unit& u) const { return (const char*)Bt + (size_t)u.pn * 2 * hB() + (size_t)(u.pm >> gshift) * goff; }
; #define PG8_BAR __builtin_amdgcn_s_barrier()
;     __device__ __forceinline__ void operator()(const f32x4 (&acc)[2][2][4][2], const Unit& u, int wr, int wc, int fr, int fq) const {
;     ...
;         float rsv[2][4];
; #pragma unroll
;         for (int ai = 0; ai < 2; ++ai)
; #pragma unroll
;             for (int m = 0; m < 4; ++m) rsv[ai][m] = RS ? rs[row0 + ai * HALF + m * 16] : 1.0f;
;     ...
;     for (int i = 0; i < 2; ++i) { int R, C; stage_rc(tid * 16 + i * 8192, R, C); const int Rb = Epi::PERM ? ((R & ~31) + perm32(R & 31)) : R;
;         voffA[i] = g.voffA(R, C); voffB[i] = g.voffB(Rb, C); }
;     const size_t kstep = (size_t)(BK * 2);
;     const size_t hstepA = g.hA(), hstepB = g.hB();
;     const unsigned ldsw = (unsigned)wid * 1024u;
;     const int aoff = lds_byte(wr * 64 + fr, fq * 8), boff = lds_byte(wc * 32 + fr, fq * 8);
;     ...
;     Unit cur, nxt; int ui = 0;
;     if (!S.next(0, cur)) return;
;     f32x4 acc[2][2][4][2];
; #pragma unroll
;     for (int a = 0; a < 2; ++a)
; #pragma unroll
;         for (int b = 0; b < 2; ++b)
; #pragma unroll
;             for (int m = 0; m < 4; ++m)
; #pragma unroll
;                 for (int n = 0; n < 2; ++n) acc[a][b][m][n] = (f32x4){0.f, 0.f, 0.f, 0.f};
;     bf16x8 At[4][2], B0[2][2], B1[2][2];
;     const char* cA = g.a(cur); const char* cB = g.b(cur);
;     S.a_ready(cur);
;     PG8_STAGE(PG8_SB(0, 0), cB, voffB); PG8_STAGE(PG8_SB(0, 1), cB + hstepB, voffB); PG8_STAGE(PG8_SA(0, 0), cA, voffA); PG8_STAGE(PG8_SA(0, 1), cA + hstepA, voffA);
;     if (wr == 1) PG8_BAR;
;     PG8_WAIT_V(2); PG8_BAR;
;     PG8_STAGE(PG8_SB(1, 0), cB + kstep, voffB); PG8_STAGE(PG8_SA(1, 0), cA + kstep, voffA); PG8_STAGE(PG8_SB(1, 1), cB + hstepB + kstep, voffB);
.LBB0_169:
	v_writelane_b32 v254, s38, 12
	s_lshr_b32 s5, s48, 8
	s_lshl_b32 s33, s49, 10
	v_writelane_b32 v254, s39, 13
	v_writelane_b32 v254, s48, 14
	s_lshl_b32 s48, s5, 6
	v_writelane_b32 v254, s5, 16
	s_lshl_b32 s5, s5, 13
	v_writelane_b32 v254, s5, 18
	s_lshl_b32 s5, s49, 5
	s_and_b32 s50, s5, 0x60
	s_lshr_b32 s5, s50, 3
	s_add_u32 s10, s94, 0xa400000
	v_writelane_b32 v254, s5, 19
	s_addc_u32 s11, s95, 0
	v_writelane_b32 v254, s10, 20
	v_cndmask_b32_e64 v0, 0, 1, s[8:9]
	s_add_u32 s84, s94, 0xe400000
	v_writelane_b32 v254, s11, 21
	v_cmp_ne_u32_e64 s[10:11], 1, v0
	s_addc_u32 s85, s95, 0
	s_andn2_b64 vcc, exec, s[8:9]
	v_writelane_b32 v254, s10, 22
	s_nop 1
	v_writelane_b32 v254, s11, 23
	s_cbranch_vccnz .LBB0_285
	v_lshl_add_u32 v0, v8, 4, s33
	v_ashrrev_i32_e32 v1, 31, v0
	v_lshrrev_b32_e32 v1, 22, v1
	v_add_u32_e32 v1, v0, v1
	v_ashrrev_i32_e32 v1, 10, v1
	v_mul_i32_i24_e32 v2, 0x400, v1
	v_sub_u32_e32 v2, v0, v2
	v_lshrrev_b32_e32 v3, 4, v2
	v_bitop3_b32 v2, v3, v2, 32 bitop3:0x6c
	v_ashrrev_i32_e32 v4, 31, v2
	v_lshrrev_b32_e32 v4, 26, v4
	v_lshlrev_b32_e32 v3, 3, v1
	v_add_u32_e32 v4, v2, v4
	v_and_b32_e32 v3, -16, v3
	v_ashrrev_i32_e32 v5, 6, v4
	v_and_b32_e32 v4, 0xc0, v4
	v_add_u32_e32 v3, v5, v3
	v_sub_u32_e32 v2, v2, v4
	v_mov_b32_e32 v4, 1
	v_lshlrev_b32_e32 v1, 5, v1
	v_ashrrev_i16_sdwa v2, v4, sext(v2) dst_sel:DWORD dst_unused:UNUSED_PAD src0_sel:DWORD src1_sel:BYTE_0
	v_lshlrev_b32_e32 v6, 1, v3
	v_lshrrev_b32_e32 v7, 2, v3
	v_and_b32_e32 v5, 3, v5
	s_mov_b32 s5, 0xfffe0
	v_and_b32_e32 v1, 32, v1
	v_bfe_i32 v2, v2, 0, 16
	v_and_b32_e32 v6, 24, v6
	v_and_b32_e32 v7, 4, v7
	v_and_or_b32 v5, v3, s5, v5
	v_or3_b32 v5, v5, v7, v6
	v_add_lshl_u32 v1, v1, v2, 1
	v_add_u32_e32 v0, 0x2000, v0
	v_lshl_add_u32 v128, v3, 12, v1
	v_lshl_add_u32 v130, v5, 12, v1
	v_ashrrev_i32_e32 v1, 31, v0
	v_lshrrev_b32_e32 v1, 22, v1
	v_add_u32_e32 v1, v0, v1
	v_ashrrev_i32_e32 v1, 10, v1
	v_mul_i32_i24_e32 v2, 0x400, v1
	v_sub_u32_e32 v0, v0, v2
	v_lshrrev_b32_e32 v2, 4, v0
	v_bitop3_b32 v0, v2, v0, 32 bitop3:0x6c
	v_ashrrev_i32_e32 v3, 31, v0
	v_lshrrev_b32_e32 v3, 26, v3
	v_lshlrev_b32_e32 v2, 3, v1
	v_add_u32_e32 v3, v0, v3
	v_and_b32_e32 v2, -16, v2
	v_ashrrev_i32_e32 v5, 6, v3
	v_and_b32_e32 v3, 0xffc0, v3
	v_add_u32_e32 v2, v5, v2
	v_sub_u32_e32 v0, v0, v3
	v_and_b32_e32 v5, 3, v5
	v_lshrrev_b16_e32 v3, 7, v0
	v_and_or_b32 v5, v2, s5, v5
	s_ashr_i32 s7, s6, 31
	s_ashr_i32 s5, s4, 31
	v_and_b32_e32 v3, 1, v3
	s_lshl_b64 s[8:9], s[6:7], 20
	s_lshl_b64 s[10:11], s[4:5], 20
	v_add_u16_e32 v0, v0, v3
	s_add_u32 s30, s24, s10
	v_lshlrev_b32_e32 v1, 5, v1
	v_ashrrev_i16_sdwa v0, v4, sext(v0) dst_sel:DWORD dst_unused:UNUSED_PAD src0_sel:DWORD src1_sel:BYTE_0
	v_lshlrev_b32_e32 v3, 1, v2
	v_lshrrev_b32_e32 v4, 2, v2
	s_addc_u32 s31, s25, s11
	s_add_i32 s38, s33, 0
	v_and_b32_e32 v1, 32, v1
	v_bfe_i32 v0, v0, 0, 16
	v_and_b32_e32 v3, 24, v3
	v_and_b32_e32 v4, 4, v4
	s_add_u32 s98, s94, 0x100000
	s_addc_u32 s99, s95, 0
	s_lshl_b32 s100, s6, 8
	s_add_i32 s100, s100, s48
	v_and_or_b32 v248, v8, 15, s100
	v_mov_b32_e32 v249, 0
	v_lshl_add_u64 v[248:249], v[248:249], 2, s[98:99]
	global_load_dword v240, v[248:249], off
	global_load_dword v241, v[248:249], off offset:64
	global_load_dword v242, v[248:249], off offset:128
	global_load_dword v243, v[248:249], off offset:192
	global_load_dword v244, v[248:249], off offset:512
	global_load_dword v245, v[248:249], off offset:576
	global_load_dword v246, v[248:249], off offset:640
	global_load_dword v247, v[248:249], off offset:704
	s_add_i32 m0, s38, 0x10000
	v_or3_b32 v3, v5, v4, v3
	v_add_lshl_u32 v0, v1, v0, 1
	global_load_lds_dwordx4 v130, s[30:31]
	s_add_i32 m0, s38, 0x12000
	v_lshl_add_u32 v134, v3, 12, v0
	s_add_u32 s10, s30, 0x80000
	global_load_lds_dwordx4 v134, s[30:31]
	s_addc_u32 s11, s31, 0
	s_add_i32 m0, s38, 0x14000
	v_lshl_add_u32 v132, v2, 12, v0
	global_load_lds_dwordx4 v130, s[10:11]
	s_add_i32 m0, s38, 0x16000
	v_mov_b32_e32 v131, 0
	global_load_lds_dwordx4 v134, s[10:11]
	v_readlane_b32 s10, v254, 20
	v_readlane_b32 s11, v254, 21
	s_add_u32 s28, s10, s8
	s_addc_u32 s29, s11, s9
	s_add_i32 s39, s38, 0x2000
	s_mov_b32 m0, s38
	s_add_u32 s8, s28, 0x80000
	global_load_lds_dwordx4 v128, s[28:29]
	s_mov_b32 m0, s39
	s_addc_u32 s9, s29, 0
	s_add_i32 s52, s38, 0x4000
	global_load_lds_dwordx4 v132, s[28:29]
	s_mov_b32 m0, s52
	s_add_i32 s53, s38, 0x6000
	global_load_lds_dwordx4 v128, s[8:9]
	s_mov_b32 m0, s53
	v_readlane_b32 s5, v254, 16
	global_load_lds_dwordx4 v132, s[8:9]
	s_add_u32 s98, s30, 0x80
	s_addc_u32 s99, s31, 0
	s_add_i32 m0, s38, 0x18000
	s_nop 0
	global_load_lds_dwordx4 v130, s[98:99]
	s_add_i32 m0, s38, 0x1a000
	s_nop 0
	global_load_lds_dwordx4 v134, s[98:99]
	s_add_u32 s98, s28, 0x80
	s_addc_u32 s99, s29, 0
	s_add_i32 m0, s38, 0x8000
	s_nop 0
	global_load_lds_dwordx4 v128, s[98:99]
	s_add_i32 m0, s38, 0xa000
	s_nop 0
	global_load_lds_dwordx4 v132, s[98:99]
	s_add_u32 s98, s30, 0x80080
	s_addc_u32 s99, s31, 0
	s_add_i32 m0, s38, 0x1c000
	s_nop 0
	global_load_lds_dwordx4 v130, s[98:99]
	s_add_i32 m0, s38, 0x1e000
	s_nop 0
	global_load_lds_dwordx4 v134, s[98:99]
	v_mov_b32_e32 v135, v131
	v_mov_b32_e32 v129, v131
	v_mov_b32_e32 v133, v131
	s_cmp_eq_u32 s5, 1
	s_mov_b32 s54, 0
	v_lshl_add_u64 v[4:5], s[30:31], 0, v[130:131]
	v_lshl_add_u64 v[2:3], s[30:31], 0, v[134:135]
	v_lshl_add_u64 v[0:1], s[28:29], 0, v[128:129]
	s_cselect_b64 s[10:11], -1, 0
	s_cmp_lg_u32 s5, 1
	v_lshl_add_u64 v[6:7], s[28:29], 0, v[132:133]
	s_cbranch_scc1 .LBB0_172
	s_barrier
;     __device__ __forceinline__ unsigned voffA(int R, int C) const { return (unsigned)(R * lda + C) * 2u; }
;     __device__ __forceinline__ unsigned voffB(int R, int C) const { return (unsigned)(R * ldb + C) * 2u; }
;     __device__ __forceinline__ unsigned voffA(int R, int C) const { return (unsigned)(R * 256 + C) * 2u; }
;     __device__ __forceinline__ unsigned voffB(int R, int C) const { return (unsigned)((256 * (R & 15) + (R >> 4)) * 1024 + C) * 2u; }
;     __device__ __forceinline__ unsigned voffA(int R, int C) const { return (unsigned)(R * 512 + C) * 2u; }
;     __device__ __forceinline__ unsigned voffB(int R, int C) const { return (unsigned)(R * 8192 + C) * 2u; }
; #define PG8_STAGE(bufoff, gbase, voff) do { _Pragma("unroll") for (int _i = 0; _i < 2; ++_i) { const unsigned _vo = (voff)[_i]; \
;         __builtin_amdgcn_global_load_lds((const PG8_GAS unsigned*)((const PG8_GAS char*)(gbase) + _vo), (PG8_LAS unsigned*)(lds + (bufoff) + ldsw + _i * 8192), 16, 0, 0); } } while (0)
; #define PG8_WAIT_V(n) asm volatile("s_waitcnt vmcnt(" #n ")" ::: "memory")
; #define PG8_BAR __builtin_amdgcn_s_barrier()
;     ...
;     const unsigned ldsw = (unsigned)wid * 1024u;
;     const int aoff = lds_byte(wr * 64 + fr, fq * 8), boff = lds_byte(wc * 32 + fr, fq * 8);
;     ...
;     PG8_STAGE(PG8_SB(0, 0), cB, voffB); PG8_STAGE(PG8_SB(0, 1), cB + hstepB, voffB); PG8_STAGE(PG8_SA(0, 0), cA, voffA); PG8_STAGE(PG8_SA(0, 1), cA + hstepA, voffA);
;     if (wr == 1) PG8_BAR;
;     PG8_WAIT_V(2); PG8_BAR;
;     PG8_STAGE(PG8_SB(1, 0), cB + kstep, voffB); PG8_STAGE(PG8_SA(1, 0), cA + kstep, voffA); PG8_STAGE(PG8_SB(1, 1), cB + hstepB + kstep, voffB);
;     PG8_WAIT_V(6); PG8_BAR;
.LBB0_172:
	s_add_u32 s12, s94, 0x100000
	s_mov_b64 s[8:9], 0x80
	s_addc_u32 s13, s95, 0
	s_add_i32 m0, s38, 0x18000
	v_lshl_add_u64 v[4:5], v[4:5], 0, s[8:9]
	s_waitcnt vmcnt(8)
	s_barrier
	v_lshl_add_u64 v[2:3], v[2:3], 0, s[8:9]
	s_add_i32 m0, s38, 0x1a000
	s_add_i32 s14, s38, 0x8000
	v_lshl_add_u64 v[0:1], v[0:1], 0, s[8:9]
	s_mov_b32 m0, s14
	s_add_i32 s15, s38, 0xa000
	v_lshl_add_u64 v[0:1], v[6:7], 0, s[8:9]
	s_add_u32 s8, s30, 0x80080
	s_mov_b32 m0, s15
	s_addc_u32 s9, s31, 0
	s_add_i32 m0, s38, 0x1c000
	v_lshl_add_u64 v[0:1], s[8:9], 0, v[130:131]
	v_lshl_add_u64 v[0:1], s[8:9], 0, v[134:135]
	s_add_i32 m0, s38, 0x1e000
	v_and_b32_e32 v4, 48, v8
	v_and_b32_e32 v0, 15, v8
	v_or_b32_e32 v1, s48, v0
	v_lshlrev_b32_e32 v3, 6, v1
	s_movk_i32 s5, 0x3c0
	v_ashrrev_i32_e32 v2, 6, v8
	v_and_or_b32 v3, v3, s5, v4
	v_readlane_b32 s5, v254, 18
	v_lshlrev_b32_e32 v1, 2, v1
	v_and_b32_e32 v1, 32, v1
	v_lshl_add_u32 v5, v2, 10, s5
	v_readlane_b32 s5, v254, 19
	v_bitop3_b32 v1, v3, v5, v1 bitop3:0xde
	v_lshlrev_b32_e32 v3, 2, v8
	v_add_lshl_u32 v2, v2, s5, 10
	v_readlane_b32 s5, v254, 14
	v_lshl_or_b32 v0, v0, 6, v4
	v_and_b32_e32 v3, 32, v3
	s_waitcnt vmcnt(6)
	s_cmpk_lt_u32 s5, 0x100
	v_bitop3_b32 v129, v0, v2, v3 bitop3:0xde
	s_cselect_b64 s[16:17], -1, 0
	s_add_i32 s57, 0, 0x10000
	s_add_i32 s60, 0, 0x14000
	s_ashr_i32 s55, s3, 31
	s_ashr_i32 s56, s2, 31
	v_mov_b64_e32 v[136:137], 0x400
	v_mov_b64_e32 v[138:139], 0x3ff
	v_add_u32_e32 v133, s57, v129
	v_add_u32_e32 v135, s60, v129
	v_add_u32_e32 v164, 0, v1
	v_mov_b32_e32 v165, 0x3e0293ee
	v_mov_b32_e32 v166, v130
	s_barrier
	v_lshrrev_b32_e32 v250, 4, v8
	v_and_b32_e32 v251, 15, v8
	v_lshlrev_b32_e32 v250, 17, v250
	v_lshl_or_b32 v250, v251, 3, v250
	v_readlane_b32 s98, v254, 0
	v_readlane_b32 s99, v254, 1
	s_sub_u32 s98, s98, 0x58
	s_subb_u32 s99, s99, 0
	s_load_dwordx2 s[100:101], s[98:99], 0x38
	s_waitcnt lgkmcnt(0)
	v_writelane_b32 v252, s100, 0
	v_writelane_b32 v252, s101, 1
	s_add_u32 s98, s94, 0x4400000
	s_addc_u32 s99, s95, 0
	v_writelane_b32 v252, s98, 2
	v_writelane_b32 v252, s99, 3
	s_lshl_b32 s98, s2, 3
	s_add_i32 s98, s98, s49
	s_and_b32 s98, s98, 0x7ff
	v_writelane_b32 v252, s98, 5
	s_branch .LBB0_175

;     __device__ __forceinline__ unsigned voffA(int R, int C) const { return (unsigned)(R * lda + C) * 2u; }
;     __device__ __forceinline__ unsigned voffB(int R, int C) const { return (unsigned)(R * ldb + C) * 2u; }
;     __device__ __forceinline__ size_t hA() const { return (size_t)HALF * lda * 2; }
;     __device__ __forceinline__ size_t hB() const { return (size_t)HALF * ldb * 2; }
;     __device__ __forceinline__ const char* a(const Unit& u) const { return (const char*)A + (size_t)u.pm * 2 * hA(); }
;     __device__ __forceinline__ const char* b(const Unit& u) const { return (const char*)Bt + (size_t)u.pn * 2 * hB() + (size_t)(u.pm >> gshift) * goff; }
; #define PG8_BAR __builtin_amdgcn_s_barrier()
;     __device__ __forceinline__ void operator()(const f32x4 (&acc)[2][2][4][2], const Unit& u, int wr, int wc, int fr, int fq) const {
;     ...
;         float rsv[2][4];
; #pragma unroll
;         for (int ai = 0; ai < 2; ++ai)
; #pragma unroll
;             for (int m = 0; m < 4; ++m) rsv[ai][m] = RS ? rs[row0 + ai * HALF + m * 16] : 1.0f;
;     ...
;     for (int i = 0; i < 2; ++i) { int R, C; stage_rc(tid * 16 + i * 8192, R, C); const int Rb = Epi::PERM ? ((R & ~31) + perm32(R & 31)) : R;
;         voffA[i] = g.voffA(R, C); voffB[i] = g.voffB(Rb, C); }
;     const size_t kstep = (size_t)(BK * 2);
;     const size_t hstepA = g.hA(), hstepB = g.hB();
;     const unsigned ldsw = (unsigned)wid * 1024u;
;     const int aoff = lds_byte(wr * 64 + fr, fq * 8), boff = lds_byte(wc * 32 + fr, fq * 8);
;     ...
;     Unit cur, nxt; int ui = 0;
;     if (!S.next(0, cur)) return;
;     f32x4 acc[2][2][4][2];
; #pragma unroll
;     for (int a = 0; a < 2; ++a)
; #pragma unroll
;         for (int b = 0; b < 2; ++b)
; #pragma unroll
;             for (int m = 0; m < 4; ++m)
; #pragma unroll
;                 for (int n = 0; n < 2; ++n) acc[a][b][m][n] = (f32x4){0.f, 0.f, 0.f, 0.f};
;     bf16x8 At[4][2], B0[2][2], B1[2][2];
;     const char* cA = g.a(cur); const char* cB = g.b(cur);
;     S.a_ready(cur);
;     PG8_STAGE(PG8_SB(0, 0), cB, voffB); PG8_STAGE(PG8_SB(0, 1), cB + hstepB, voffB); PG8_STAGE(PG8_SA(0, 0), cA, voffA); PG8_STAGE(PG8_SA(0, 1), cA + hstepA, voffA);
;     if (wr == 1) PG8_BAR;
;     PG8_WAIT_V(2); PG8_BAR;
;     PG8_STAGE(PG8_SB(1, 0), cB + kstep, voffB); PG8_STAGE(PG8_SA(1, 0), cA + kstep, voffA); PG8_STAGE(PG8_SB(1, 1), cB + hstepB + kstep, voffB);
.LBB0_703:
	v_readlane_b32 s0, v254, 40
	v_readlane_b32 s1, v254, 41
	s_and_b64 s[0:1], s[0:1], s[20:21]
	s_and_b64 s[0:1], s[0:1], exec
	v_readlane_b32 s0, v254, 20
	v_readlane_b32 s1, v254, 21
	s_cselect_b32 s77, s1, s69
	s_cselect_b32 s76, s0, s68
	s_lshl_b64 s[0:1], s[78:79], 12
	s_add_u32 s30, s74, s0
	s_mov_b32 s0, s70
	s_addc_u32 s31, s75, s1
	v_mbcnt_lo_u32_b32 v0, s0, 0
	v_mbcnt_hi_u32_b32 v0, s0, v0
	v_readlane_b32 s0, v254, 22
	v_readlane_b32 s1, v254, 23
	s_and_b64 vcc, exec, s[0:1]
	s_cbranch_vccnz .LBB0_723
	v_readlane_b32 s98, v254, 36
	v_readlane_b32 s99, v254, 37
	s_lshl_b64 s[100:101], s[78:79], 2
	s_add_u32 s98, s98, s100
	s_addc_u32 s99, s99, s101
	v_readlane_b32 s100, v255, 19
	s_lshl_b32 s100, s100, 8
	s_add_i32 s100, s100, s48
	v_and_or_b32 v248, v0, 15, s100
	v_mov_b32_e32 v249, 0
	v_lshl_add_u64 v[248:249], v[248:249], 2, s[98:99]
	global_load_dword v240, v[248:249], off
	global_load_dword v241, v[248:249], off offset:64
	global_load_dword v242, v[248:249], off offset:128
	global_load_dword v243, v[248:249], off offset:192
	global_load_dword v244, v[248:249], off offset:512
	global_load_dword v245, v[248:249], off offset:576
	global_load_dword v246, v[248:249], off offset:640
	global_load_dword v247, v[248:249], off offset:704
	v_lshl_add_u32 v1, v0, 4, s33
	v_ashrrev_i32_e32 v2, 31, v1
	v_lshrrev_b32_e32 v2, 22, v2
	v_add_u32_e32 v2, v1, v2
	v_ashrrev_i32_e32 v2, 10, v2
	v_mul_i32_i24_e32 v3, 0x400, v2
	v_sub_u32_e32 v3, v1, v3
	v_lshrrev_b32_e32 v4, 4, v3
	v_bitop3_b32 v3, v4, v3, 32 bitop3:0x6c
	v_ashrrev_i32_e32 v5, 31, v3
	v_lshrrev_b32_e32 v5, 26, v5
	v_lshlrev_b32_e32 v4, 3, v2
	v_add_u32_e32 v5, v3, v5
	v_and_b32_e32 v4, -16, v4
	v_ashrrev_i32_e32 v6, 6, v5
	v_and_b32_e32 v5, 0xc0, v5
	v_add_u32_e32 v4, v6, v4
	v_sub_u32_e32 v3, v3, v5
	v_lshlrev_b32_e32 v2, 5, v2
	v_ashrrev_i16_sdwa v3, v228, sext(v3) dst_sel:DWORD dst_unused:UNUSED_PAD src0_sel:DWORD src1_sel:BYTE_0
	v_lshlrev_b32_e32 v5, 1, v4
	v_lshrrev_b32_e32 v7, 2, v4
	v_and_b32_e32 v6, 3, v6
	s_mov_b32 s0, 0xfffe0
	v_and_b32_e32 v2, 32, v2
	v_bfe_i32 v3, v3, 0, 16
	v_and_b32_e32 v5, 24, v5
	v_and_b32_e32 v7, 4, v7
	v_and_or_b32 v6, v4, s0, v6
	v_or3_b32 v5, v6, v7, v5
	v_add_lshl_u32 v2, v2, v3, 1
	v_add_u32_e32 v1, 0x2000, v1
	v_lshl_add_u32 v128, v4, 12, v2
	v_lshl_add_u32 v192, v5, 12, v2
	v_ashrrev_i32_e32 v2, 31, v1
	v_lshrrev_b32_e32 v2, 22, v2
	v_add_u32_e32 v2, v1, v2
	v_ashrrev_i32_e32 v2, 10, v2
	v_mul_i32_i24_e32 v3, 0x400, v2
	v_sub_u32_e32 v1, v1, v3
	v_lshrrev_b32_e32 v3, 4, v1
	v_bitop3_b32 v1, v3, v1, 32 bitop3:0x6c
	v_ashrrev_i32_e32 v4, 31, v1
	v_lshrrev_b32_e32 v4, 26, v4
	v_add_u32_e32 v4, v1, v4
	v_ashrrev_i32_e32 v5, 6, v4
	v_and_b32_e32 v4, 0xffc0, v4
	v_sub_u32_e32 v1, v1, v4
	v_lshlrev_b32_e32 v3, 3, v2
	v_lshrrev_b16_e32 v4, 7, v1
	v_and_b32_e32 v3, -16, v3
	v_and_b32_e32 v4, 1, v4
	v_add_u32_e32 v3, v5, v3
	v_add_u16_e32 v1, v1, v4
	v_lshlrev_b32_e32 v2, 5, v2
	v_ashrrev_i16_sdwa v1, v228, sext(v1) dst_sel:DWORD dst_unused:UNUSED_PAD src0_sel:DWORD src1_sel:BYTE_0
	v_lshlrev_b32_e32 v4, 1, v3
	v_lshrrev_b32_e32 v6, 2, v3
	v_and_b32_e32 v5, 3, v5
	v_and_b32_e32 v2, 32, v2
	v_bfe_i32 v1, v1, 0, 16
	v_and_b32_e32 v4, 24, v4
	v_and_b32_e32 v6, 4, v6
	v_and_or_b32 v5, v3, s0, v5
	s_add_i32 s0, s33, 0
	v_readlane_b32 s20, v255, 25
	v_or3_b32 v4, v5, v6, v4
	v_add_lshl_u32 v1, v2, v1, 1
	s_add_i32 m0, s0, 0x10000
	v_readlane_b32 s21, v255, 26
	v_lshl_add_u32 v132, v4, 12, v1
	v_lshl_add_u32 v130, v3, 12, v1
	v_cmp_ne_u32_e64 s[38:39], 1, v226
	s_nop 1
	global_load_lds_dwordx4 v192, s[20:21]
	s_add_i32 m0, s0, 0x12000
	s_nop 0
	global_load_lds_dwordx4 v132, s[20:21]
	v_readlane_b32 s20, v255, 23
	s_add_i32 m0, s0, 0x14000
	v_readlane_b32 s21, v255, 24
	s_nop 4
	global_load_lds_dwordx4 v192, s[20:21]
	s_add_i32 m0, s0, 0x16000
	s_nop 0
	global_load_lds_dwordx4 v132, s[20:21]
	v_readlane_b32 s20, v255, 21
	v_readlane_b32 s21, v255, 22
	s_add_u32 s46, s30, s20
	s_addc_u32 s47, s31, s21
	s_add_i32 s1, s0, 0x2000
	s_mov_b32 m0, s0
	s_add_u32 s20, s46, 0x80000
	global_load_lds_dwordx4 v128, s[46:47]
	s_mov_b32 m0, s1
	s_addc_u32 s21, s47, 0
	s_add_i32 s34, s0, 0x4000
	global_load_lds_dwordx4 v130, s[46:47]
	s_mov_b32 m0, s34
	s_add_i32 s35, s0, 0x6000
	global_load_lds_dwordx4 v128, s[20:21]
	s_mov_b32 m0, s35
	s_nop 0
	global_load_lds_dwordx4 v130, s[20:21]
	v_readlane_b32 s98, v255, 25
	v_readlane_b32 s99, v255, 26
	s_add_u32 s98, s98, 0x80
	s_addc_u32 s99, s99, 0
	s_add_i32 m0, s0, 0x18000
	s_nop 0
	global_load_lds_dwordx4 v192, s[98:99]
	s_add_i32 m0, s0, 0x1a000
	s_nop 0
	global_load_lds_dwordx4 v132, s[98:99]
	s_add_u32 s98, s46, 0x80
	s_addc_u32 s99, s47, 0
	s_add_i32 m0, s0, 0x8000
	s_nop 0
	global_load_lds_dwordx4 v128, s[98:99]
	s_add_i32 m0, s0, 0xa000
	s_nop 0
	global_load_lds_dwordx4 v130, s[98:99]
	v_readlane_b32 s98, v255, 27
	v_readlane_b32 s99, v255, 28
	s_add_i32 m0, s0, 0x1c000
	s_nop 0
	global_load_lds_dwordx4 v192, s[98:99]
	s_add_i32 m0, s0, 0x1e000
	s_nop 0
	global_load_lds_dwordx4 v132, s[98:99]
	v_readlane_b32 s20, v254, 26
	v_readlane_b32 s21, v254, 27
	s_andn2_b64 vcc, exec, s[20:21]
	s_cbranch_vccnz .LBB0_706
	s_barrier
.LBB0_706:
	v_and_b32_e32 v1, 15, v0
	s_lshl_b64 s[20:21], s[78:79], 2
	v_readlane_b32 s22, v254, 36
	v_or_b32_e32 v10, s48, v1
	v_readlane_b32 s26, v255, 25
	s_add_u32 s24, s22, s20
	v_lshlrev_b32_e32 v12, 6, v10
	v_and_b32_e32 v13, 48, v0
	s_movk_i32 s20, 0x3c0
	v_readlane_b32 s27, v255, 26
	v_readlane_b32 s23, v254, 37
	v_ashrrev_i32_e32 v11, 6, v0
	v_and_or_b32 v12, v12, s20, v13
	v_readlane_b32 s20, v254, 19
	v_lshlrev_b32_e32 v0, 2, v0
	v_lshl_add_u64 v[2:3], s[26:27], 0, v[192:193]
	v_mov_b32_e32 v133, v193
	v_mov_b32_e32 v129, v193
	s_addc_u32 s25, s23, s21
	v_lshl_add_u32 v14, v11, 10, s95
	v_lshl_or_b32 v1, v1, 6, v13
	v_add_lshl_u32 v11, v11, s20, 10
	v_and_b32_e32 v0, 32, v0
	s_mov_b64 s[20:21], 0x80
	v_lshl_add_u64 v[4:5], s[26:27], 0, v[132:133]
	v_lshl_add_u64 v[6:7], s[46:47], 0, v[128:129]
	v_bitop3_b32 v129, v1, v11, v0 bitop3:0xde
	v_lshl_add_u64 v[0:1], v[2:3], 0, s[20:21]
	s_add_i32 m0, s0, 0x18000
	v_mov_b32_e32 v131, v193
	s_waitcnt vmcnt(8)
	s_barrier
	v_lshl_add_u64 v[0:1], v[4:5], 0, s[20:21]
	s_add_i32 m0, s0, 0x1a000
	s_add_i32 s54, s0, 0x8000
	v_lshl_add_u64 v[8:9], s[46:47], 0, v[130:131]
	v_lshl_add_u64 v[0:1], v[6:7], 0, s[20:21]
	s_mov_b32 m0, s54
	s_add_i32 s55, s0, 0xa000
	v_lshl_add_u64 v[0:1], v[8:9], 0, s[20:21]
	v_readlane_b32 s20, v255, 27
	s_mov_b32 m0, s55
	v_readlane_b32 s21, v255, 28
	s_nop 0
	v_lshl_add_u64 v[0:1], s[20:21], 0, v[192:193]
	s_add_i32 m0, s0, 0x1c000
	v_lshlrev_b32_e32 v10, 2, v10
	v_lshl_add_u64 v[0:1], s[20:21], 0, v[132:133]
	s_add_i32 m0, s0, 0x1e000
	v_and_b32_e32 v10, 32, v10
	s_waitcnt vmcnt(6)
	v_bitop3_b32 v10, v12, v14, v10 bitop3:0xde
	v_readlane_b32 s20, v255, 19
	s_mov_b32 s73, 0
	v_add_u32_e32 v131, 0, v10
	v_readlane_b32 s75, v255, 18
	s_mov_b32 s74, s20
	s_barrier
	v_readlane_b32 s21, v255, 20
	s_branch .LBB0_709

;     __device__ __forceinline__ unsigned voffA(int R, int C) const { return (unsigned)(R * lda + C) * 2u; }
;     __device__ __forceinline__ unsigned voffB(int R, int C) const { return (unsigned)(R * ldb + C) * 2u; }
;     __device__ __forceinline__ size_t hA() const { return (size_t)HALF * lda * 2; }
;     __device__ __forceinline__ size_t hB() const { return (size_t)HALF * ldb * 2; }
;     __device__ __forceinline__ const char* a(const Unit& u) const { return (const char*)A + (size_t)u.pm * 2 * hA(); }
;     __device__ __forceinline__ const char* b(const Unit& u) const { return (const char*)Bt + (size_t)u.pn * 2 * hB() + (size_t)(u.pm >> gshift) * goff; }
;     __device__ __forceinline__ unsigned voffA(int R, int C) const { return (unsigned)(R * 256 + C) * 2u; }
;     __device__ __forceinline__ unsigned voffB(int R, int C) const { return (unsigned)((256 * (R & 15) + (R >> 4)) * 1024 + C) * 2u; }
;     __device__ __forceinline__ size_t hA() const { return (size_t)HALF * 256 * 2; }
; #define PG8_WAIT_V(n) asm volatile("s_waitcnt vmcnt(" #n ")" ::: "memory")
;     ...
;     for (int i = 0; i < 2; ++i) { int R, C; stage_rc(tid * 16 + i * 8192, R, C); const int Rb = Epi::PERM ? ((R & ~31) + perm32(R & 31)) : R;
;         voffA[i] = g.voffA(R, C); voffB[i] = g.voffB(Rb, C); }
;     const size_t kstep = (size_t)(BK * 2);
;     const size_t hstepA = g.hA(), hstepB = g.hB();
;     const unsigned ldsw = (unsigned)wid * 1024u;
;     const int aoff = lds_byte(wr * 64 + fr, fq * 8), boff = lds_byte(wc * 32 + fr, fq * 8);
;     ...
;     Unit cur, nxt; int ui = 0;
;     if (!S.next(0, cur)) return;
;     f32x4 acc[2][2][4][2];
; #pragma unroll
;     for (int a = 0; a < 2; ++a)
; #pragma unroll
;         for (int b = 0; b < 2; ++b)
; #pragma unroll
;             for (int m = 0; m < 4; ++m)
; #pragma unroll
;                 for (int n = 0; n < 2; ++n) acc[a][b][m][n] = (f32x4){0.f, 0.f, 0.f, 0.f};
;     bf16x8 At[4][2], B0[2][2], B1[2][2];
;     const char* cA = g.a(cur); const char* cB = g.b(cur);
;     S.a_ready(cur);
;     PG8_STAGE(PG8_SB(0, 0), cB, voffB); PG8_STAGE(PG8_SB(0, 1), cB + hstepB, voffB); PG8_STAGE(PG8_SA(0, 0), cA, voffA); PG8_STAGE(PG8_SA(0, 1), cA + hstepA, voffA);
;     if (wr == 1) PG8_BAR;
;     PG8_WAIT_V(2); PG8_BAR;
;     PG8_STAGE(PG8_SB(1, 0), cB + kstep, voffB); PG8_STAGE(PG8_SA(1, 0), cA + kstep, voffA); PG8_STAGE(PG8_SB(1, 1), cB + hstepB + kstep, voffB);
.LBB0_869:
	s_and_b64 vcc, exec, s[20:21]
	s_cbranch_vccz .LBB0_702
	s_mov_b32 s0, s70
	s_and_b64 vcc, exec, s[38:39]
	v_mbcnt_lo_u32_b32 v0, s0, 0
	v_mbcnt_hi_u32_b32 v0, s0, v0
	s_cbranch_vccnz .LBB0_702
	v_lshl_add_u32 v1, v0, 4, s33
	v_ashrrev_i32_e32 v2, 31, v1
	v_lshrrev_b32_e32 v2, 22, v2
	v_add_u32_e32 v2, v1, v2
	v_ashrrev_i32_e32 v2, 10, v2
	v_mul_i32_i24_e32 v3, 0x400, v2
	v_sub_u32_e32 v3, v1, v3
	v_lshrrev_b32_e32 v4, 4, v3
	v_bitop3_b32 v3, v4, v3, 32 bitop3:0x6c
	v_ashrrev_i32_e32 v5, 31, v3
	v_lshrrev_b32_e32 v5, 26, v5
	v_lshlrev_b32_e32 v4, 3, v2
	v_add_u32_e32 v5, v3, v5
	v_and_b32_e32 v4, -16, v4
	v_ashrrev_i32_e32 v6, 6, v5
	v_and_b32_e32 v5, 0xc0, v5
	v_add_u32_e32 v4, v6, v4
	v_sub_u32_e32 v3, v3, v5
	v_lshlrev_b32_e32 v2, 5, v2
	v_ashrrev_i16_sdwa v3, v228, sext(v3) dst_sel:DWORD dst_unused:UNUSED_PAD src0_sel:DWORD src1_sel:BYTE_0
	v_lshlrev_b32_e32 v5, 1, v4
	v_lshrrev_b32_e32 v7, 2, v4
	v_and_b32_e32 v6, 3, v6
	s_mov_b32 s0, 0x3ffe0
	v_and_b32_e32 v2, 32, v2
	v_bfe_i32 v3, v3, 0, 16
	v_and_b32_e32 v5, 24, v5
	v_and_b32_e32 v7, 4, v7
	v_and_or_b32 v6, v4, s0, v6
	v_or3_b32 v5, v6, v7, v5
	v_add_lshl_u32 v2, v2, v3, 1
	v_add_u32_e32 v1, 0x2000, v1
	v_lshl_add_u32 v202, v4, 14, v2
	v_lshl_add_u32 v192, v5, 14, v2
	v_ashrrev_i32_e32 v2, 31, v1
	v_lshrrev_b32_e32 v2, 22, v2
	v_add_u32_e32 v2, v1, v2
	v_ashrrev_i32_e32 v2, 10, v2
	v_mul_i32_i24_e32 v3, 0x400, v2
	v_sub_u32_e32 v1, v1, v3
	v_lshrrev_b32_e32 v3, 4, v1
	v_bitop3_b32 v1, v3, v1, 32 bitop3:0x6c
	v_ashrrev_i32_e32 v4, 31, v1
	v_lshrrev_b32_e32 v4, 26, v4
	v_add_u32_e32 v4, v1, v4
	v_ashrrev_i32_e32 v5, 6, v4
	v_and_b32_e32 v4, 0xffc0, v4
	v_sub_u32_e32 v1, v1, v4
	v_lshlrev_b32_e32 v3, 3, v2
	v_lshrrev_b16_e32 v4, 7, v1
	v_and_b32_e32 v3, -16, v3
	v_and_b32_e32 v4, 1, v4
	v_add_u32_e32 v3, v5, v3
	v_add_u16_e32 v1, v1, v4
	v_lshlrev_b32_e32 v2, 5, v2
	v_ashrrev_i16_sdwa v1, v228, sext(v1) dst_sel:DWORD dst_unused:UNUSED_PAD src0_sel:DWORD src1_sel:BYTE_0
	v_lshlrev_b32_e32 v4, 1, v3
	v_lshrrev_b32_e32 v6, 2, v3
	v_and_b32_e32 v5, 3, v5
	v_and_b32_e32 v2, 32, v2
	v_bfe_i32 v1, v1, 0, 16
	v_and_b32_e32 v4, 24, v4
	v_and_b32_e32 v6, 4, v6
	v_and_or_b32 v5, v3, s0, v5
	s_add_i32 s73, s33, 0
	v_readlane_b32 s0, v255, 40
	v_or3_b32 v4, v5, v6, v4
	v_add_lshl_u32 v1, v2, v1, 1
	s_add_i32 m0, s73, 0x10000
	v_readlane_b32 s1, v255, 41
	v_lshl_add_u32 v206, v4, 14, v1
	v_lshl_add_u32 v204, v3, 14, v1
	v_cmp_ne_u32_e64 s[38:39], 1, v226
	s_nop 1
	global_load_lds_dwordx4 v192, s[0:1]
	s_add_i32 m0, s73, 0x12000
	s_nop 0
	global_load_lds_dwordx4 v206, s[0:1]
	v_readlane_b32 s0, v255, 32
	s_add_i32 m0, s73, 0x14000
	v_readlane_b32 s1, v255, 33
	s_nop 4
	global_load_lds_dwordx4 v192, s[0:1]
	s_add_i32 m0, s73, 0x16000
	s_nop 0
	global_load_lds_dwordx4 v206, s[0:1]
	v_readlane_b32 s0, v255, 34
	v_readlane_b32 s1, v255, 35
	s_add_u32 s20, s76, s0
	s_addc_u32 s21, s77, s1
	s_add_i32 s34, s73, 0x2000
	s_mov_b32 m0, s73
	s_add_u32 s22, s20, 0x200000
	global_load_lds_dwordx4 v202, s[20:21]
	s_mov_b32 m0, s34
	s_addc_u32 s23, s21, 0
	s_add_i32 s35, s73, 0x4000
	global_load_lds_dwordx4 v204, s[20:21]
	s_mov_b32 m0, s35
	s_add_i32 s0, s73, 0x6000
	global_load_lds_dwordx4 v202, s[22:23]
	s_mov_b32 m0, s0
	s_nop 0
	global_load_lds_dwordx4 v204, s[22:23]
	v_readlane_b32 s98, v255, 40
	v_readlane_b32 s99, v255, 41
	s_add_u32 s98, s98, 0x80
	s_addc_u32 s99, s99, 0
	s_add_i32 m0, s73, 0x18000
	s_nop 0
	global_load_lds_dwordx4 v192, s[98:99]
	s_add_i32 m0, s73, 0x1a000
	s_nop 0
	global_load_lds_dwordx4 v206, s[98:99]
	s_add_u32 s98, s20, 0x80
	s_addc_u32 s99, s21, 0
	s_add_i32 m0, s73, 0x8000
	s_nop 0
	global_load_lds_dwordx4 v202, s[98:99]
	s_add_i32 m0, s73, 0xa000
	s_nop 0
	global_load_lds_dwordx4 v204, s[98:99]
	v_readlane_b32 s98, v255, 42
	v_readlane_b32 s99, v255, 43
	s_add_i32 m0, s73, 0x1c000
	s_nop 0
	global_load_lds_dwordx4 v192, s[98:99]
	s_add_i32 m0, s73, 0x1e000
	s_nop 0
	global_load_lds_dwordx4 v206, s[98:99]
	v_readlane_b32 s22, v254, 26
	v_readlane_b32 s23, v254, 27
	s_andn2_b64 vcc, exec, s[22:23]
	s_cbranch_vccnz .LBB0_873
	s_barrier
.LBB0_873:
	s_lshl_b64 s[22:23], s[78:79], 11
	s_lshl_b64 s[24:25], s[78:79], 3
	v_readlane_b32 s1, v255, 16
	s_add_u32 s46, s1, s24
	v_readlane_b32 s1, v255, 17
	v_and_b32_e32 v1, 15, v0
	s_addc_u32 s47, s1, s25
	v_readlane_b32 s24, v254, 2
	v_or_b32_e32 v10, s48, v1
	v_readlane_b32 s28, v255, 40
	s_lshl_b64 s[22:23], s[22:23], 2
	v_readlane_b32 s26, v254, 4
	v_lshlrev_b32_e32 v12, 6, v10
	v_and_b32_e32 v13, 48, v0
	s_movk_i32 s1, 0x3c0
	v_readlane_b32 s29, v255, 41
	v_readlane_b32 s27, v254, 5
	s_add_u32 s78, s26, s22
	v_ashrrev_i32_e32 v11, 6, v0
	v_and_or_b32 v12, v12, s1, v13
	v_readlane_b32 s1, v254, 19
	v_lshlrev_b32_e32 v0, 2, v0
	v_lshl_add_u64 v[2:3], s[28:29], 0, v[192:193]
	v_mov_b32_e32 v207, v193
	v_mov_b32_e32 v203, v193
	s_addc_u32 s79, s27, s23
	v_lshl_add_u32 v14, v11, 10, s95
	v_lshl_or_b32 v1, v1, 6, v13
	v_add_lshl_u32 v11, v11, s1, 10
	v_and_b32_e32 v0, 32, v0
	s_mov_b64 s[22:23], 0x80
	v_lshl_add_u64 v[4:5], s[28:29], 0, v[206:207]
	v_lshl_add_u64 v[6:7], s[20:21], 0, v[202:203]
	v_bitop3_b32 v203, v1, v11, v0 bitop3:0xde
	v_lshl_add_u64 v[0:1], v[2:3], 0, s[22:23]
	s_add_i32 m0, s73, 0x18000
	v_mov_b32_e32 v205, v193
	s_waitcnt vmcnt(8)
	s_barrier
	v_lshl_add_u64 v[0:1], v[4:5], 0, s[22:23]
	s_add_i32 m0, s73, 0x1a000
	s_add_i32 s1, s73, 0x8000
	v_lshl_add_u64 v[8:9], s[20:21], 0, v[204:205]
	v_lshl_add_u64 v[0:1], v[6:7], 0, s[22:23]
	s_mov_b32 m0, s1
	s_add_i32 s54, s73, 0xa000
	v_lshl_add_u64 v[0:1], v[8:9], 0, s[22:23]
	v_readlane_b32 s22, v255, 42
	s_mov_b32 m0, s54
	v_readlane_b32 s23, v255, 43
	s_nop 0
	v_lshl_add_u64 v[0:1], s[22:23], 0, v[192:193]
	s_add_i32 m0, s73, 0x1c000
	v_lshlrev_b32_e32 v10, 2, v10
	v_lshl_add_u64 v[0:1], s[22:23], 0, v[206:207]
	s_add_i32 m0, s73, 0x1e000
	v_and_b32_e32 v10, 32, v10
	s_waitcnt vmcnt(6)
	v_readlane_b32 s22, v255, 30
	v_bitop3_b32 v10, v12, v14, v10 bitop3:0xde
	v_readlane_b32 s23, v255, 31
	s_mov_b32 s55, 0
	v_add_u32_e32 v205, 0, v10
	v_readlane_b32 s74, v255, 29
	s_mov_b32 s75, s22
	s_mov_b64 s[22:23], s[28:29]
	v_readlane_b32 s25, v254, 3
	s_barrier
	s_branch .LBB0_876
